# down/out-projection GEMM k-loop and gated-residual epilogue rewritten for v_mfma_f32_16x16x32_bf16
# speedup vs baseline: 1.1194x; 1.0101x over previous
.Lrs16_epi:
	s_nop 4
	v_readlane_b32 s0, v238, 10
	v_readlane_b32 s1, v238, 11
	v_readlane_b32 s6, v238, 7
	v_readlane_b32 s8, v238, 13
	v_readlane_b32 s9, v238, 12
	v_readlane_b32 s10, v238, 16
	v_readlane_b32 s11, v238, 17
	v_readlane_b32 s12, v238, 14
	v_readlane_b32 s13, v238, 15
	v_and_b32_e32 v48, 15, v127
	v_bfe_u32 v49, v127, 4, 2
	v_lshrrev_b32_e32 v51, 6, v127
	v_lshl_add_u32 v51, v51, 5, v48
	v_add_u32_e32 v51, s5, v51
	v_lshlrev_b32_e32 v51, 2, v51
	v_add_u32_e32 v52, 64, v51
	v_lshl_add_u32 v50, v49, 2, s4
	global_load_dword v60, v51, s[0:1] offset:0
	v_add_u32_e32 v72, 0x9000, v51
	global_load_dword v61, v72, s[0:1]
	v_add_u32_e32 v72, 0x12000, v51
	global_load_dword v62, v72, s[0:1]
	global_load_dword v63, v52, s[0:1] offset:0
	v_add_u32_e32 v72, 0x9000, v52
	global_load_dword v64, v72, s[0:1]
	v_add_u32_e32 v72, 0x12000, v52
	global_load_dword v65, v72, s[0:1]
	v_mov_b32_e32 v53, s8
	v_mov_b32_e32 v54, s9
	v_mov_b32_e32 v55, s10
	v_mov_b32_e32 v56, s11
	v_mov_b32_e32 v71, 0
	v_mov_b32_e32 v66, v50
	v_cmp_gt_u32_e32 vcc, s77, v66
	v_lshlrev_b32_e32 v70, 12, v66
	v_add_u32_e32 v70, v70, v51
	v_cndmask_b32_e32 v68, v55, v53, vcc
	v_cndmask_b32_e32 v69, v56, v54, vcc
	v_lshl_add_u64 v[72:73], v[70:71], 0, v[68:69]
	global_load_dword v182, v[72:73], off
	v_add_u32_e32 v66, 1, v50
	v_cmp_gt_u32_e32 vcc, s77, v66
	v_lshlrev_b32_e32 v70, 12, v66
	v_add_u32_e32 v70, v70, v51
	v_cndmask_b32_e32 v68, v55, v53, vcc
	v_cndmask_b32_e32 v69, v56, v54, vcc
	v_lshl_add_u64 v[72:73], v[70:71], 0, v[68:69]
	global_load_dword v183, v[72:73], off
	v_add_u32_e32 v66, 2, v50
	v_cmp_gt_u32_e32 vcc, s77, v66
	v_lshlrev_b32_e32 v70, 12, v66
	v_add_u32_e32 v70, v70, v51
	v_cndmask_b32_e32 v68, v55, v53, vcc
	v_cndmask_b32_e32 v69, v56, v54, vcc
	v_lshl_add_u64 v[72:73], v[70:71], 0, v[68:69]
	global_load_dword v184, v[72:73], off
	v_add_u32_e32 v66, 3, v50
	v_cmp_gt_u32_e32 vcc, s77, v66
	v_lshlrev_b32_e32 v70, 12, v66
	v_add_u32_e32 v70, v70, v51
	v_cndmask_b32_e32 v68, v55, v53, vcc
	v_cndmask_b32_e32 v69, v56, v54, vcc
	v_lshl_add_u64 v[72:73], v[70:71], 0, v[68:69]
	global_load_dword v185, v[72:73], off
	v_mov_b32_e32 v66, v50
	v_cmp_gt_u32_e32 vcc, s77, v66
	v_lshlrev_b32_e32 v70, 12, v66
	v_add_u32_e32 v70, v70, v52
	v_cndmask_b32_e32 v68, v55, v53, vcc
	v_cndmask_b32_e32 v69, v56, v54, vcc
	v_lshl_add_u64 v[72:73], v[70:71], 0, v[68:69]
	global_load_dword v186, v[72:73], off
	v_add_u32_e32 v66, 1, v50
	v_cmp_gt_u32_e32 vcc, s77, v66
	v_lshlrev_b32_e32 v70, 12, v66
	v_add_u32_e32 v70, v70, v52
	v_cndmask_b32_e32 v68, v55, v53, vcc
	v_cndmask_b32_e32 v69, v56, v54, vcc
	v_lshl_add_u64 v[72:73], v[70:71], 0, v[68:69]
	global_load_dword v187, v[72:73], off
	v_add_u32_e32 v66, 2, v50
	v_cmp_gt_u32_e32 vcc, s77, v66
	v_lshlrev_b32_e32 v70, 12, v66
	v_add_u32_e32 v70, v70, v52
	v_cndmask_b32_e32 v68, v55, v53, vcc
	v_cndmask_b32_e32 v69, v56, v54, vcc
	v_lshl_add_u64 v[72:73], v[70:71], 0, v[68:69]
	global_load_dword v188, v[72:73], off
	v_add_u32_e32 v66, 3, v50
	v_cmp_gt_u32_e32 vcc, s77, v66
	v_lshlrev_b32_e32 v70, 12, v66
	v_add_u32_e32 v70, v70, v52
	v_cndmask_b32_e32 v68, v55, v53, vcc
	v_cndmask_b32_e32 v69, v56, v54, vcc
	v_lshl_add_u64 v[72:73], v[70:71], 0, v[68:69]
	global_load_dword v189, v[72:73], off
	v_add_u32_e32 v66, 16, v50
	v_cmp_gt_u32_e32 vcc, s77, v66
	v_lshlrev_b32_e32 v70, 12, v66
	v_add_u32_e32 v70, v70, v51
	v_cndmask_b32_e32 v68, v55, v53, vcc
	v_cndmask_b32_e32 v69, v56, v54, vcc
	v_lshl_add_u64 v[72:73], v[70:71], 0, v[68:69]
	global_load_dword v190, v[72:73], off
	v_add_u32_e32 v66, 17, v50
	v_cmp_gt_u32_e32 vcc, s77, v66
	v_lshlrev_b32_e32 v70, 12, v66
	v_add_u32_e32 v70, v70, v51
	v_cndmask_b32_e32 v68, v55, v53, vcc
	v_cndmask_b32_e32 v69, v56, v54, vcc
	v_lshl_add_u64 v[72:73], v[70:71], 0, v[68:69]
	global_load_dword v191, v[72:73], off
	v_add_u32_e32 v66, 18, v50
	v_cmp_gt_u32_e32 vcc, s77, v66
	v_lshlrev_b32_e32 v70, 12, v66
	v_add_u32_e32 v70, v70, v51
	v_cndmask_b32_e32 v68, v55, v53, vcc
	v_cndmask_b32_e32 v69, v56, v54, vcc
	v_lshl_add_u64 v[72:73], v[70:71], 0, v[68:69]
	global_load_dword v192, v[72:73], off
	v_add_u32_e32 v66, 19, v50
	v_cmp_gt_u32_e32 vcc, s77, v66
	v_lshlrev_b32_e32 v70, 12, v66
	v_add_u32_e32 v70, v70, v51
	v_cndmask_b32_e32 v68, v55, v53, vcc
	v_cndmask_b32_e32 v69, v56, v54, vcc
	v_lshl_add_u64 v[72:73], v[70:71], 0, v[68:69]
	global_load_dword v193, v[72:73], off
	v_add_u32_e32 v66, 16, v50
	v_cmp_gt_u32_e32 vcc, s77, v66
	v_lshlrev_b32_e32 v70, 12, v66
	v_add_u32_e32 v70, v70, v52
	v_cndmask_b32_e32 v68, v55, v53, vcc
	v_cndmask_b32_e32 v69, v56, v54, vcc
	v_lshl_add_u64 v[72:73], v[70:71], 0, v[68:69]
	global_load_dword v194, v[72:73], off
	v_add_u32_e32 v66, 17, v50
	v_cmp_gt_u32_e32 vcc, s77, v66
	v_lshlrev_b32_e32 v70, 12, v66
	v_add_u32_e32 v70, v70, v52
	v_cndmask_b32_e32 v68, v55, v53, vcc
	v_cndmask_b32_e32 v69, v56, v54, vcc
	v_lshl_add_u64 v[72:73], v[70:71], 0, v[68:69]
	global_load_dword v195, v[72:73], off
	v_add_u32_e32 v66, 18, v50
	v_cmp_gt_u32_e32 vcc, s77, v66
	v_lshlrev_b32_e32 v70, 12, v66
	v_add_u32_e32 v70, v70, v52
	v_cndmask_b32_e32 v68, v55, v53, vcc
	v_cndmask_b32_e32 v69, v56, v54, vcc
	v_lshl_add_u64 v[72:73], v[70:71], 0, v[68:69]
	global_load_dword v196, v[72:73], off
	v_add_u32_e32 v66, 19, v50
	v_cmp_gt_u32_e32 vcc, s77, v66
	v_lshlrev_b32_e32 v70, 12, v66
	v_add_u32_e32 v70, v70, v52
	v_cndmask_b32_e32 v68, v55, v53, vcc
	v_cndmask_b32_e32 v69, v56, v54, vcc
	v_lshl_add_u64 v[72:73], v[70:71], 0, v[68:69]
	global_load_dword v197, v[72:73], off
	v_add_u32_e32 v66, 32, v50
	v_cmp_gt_u32_e32 vcc, s77, v66
	v_lshlrev_b32_e32 v70, 12, v66
	v_add_u32_e32 v70, v70, v51
	v_cndmask_b32_e32 v68, v55, v53, vcc
	v_cndmask_b32_e32 v69, v56, v54, vcc
	v_lshl_add_u64 v[72:73], v[70:71], 0, v[68:69]
	global_load_dword v198, v[72:73], off
	v_add_u32_e32 v66, 33, v50
	v_cmp_gt_u32_e32 vcc, s77, v66
	v_lshlrev_b32_e32 v70, 12, v66
	v_add_u32_e32 v70, v70, v51
	v_cndmask_b32_e32 v68, v55, v53, vcc
	v_cndmask_b32_e32 v69, v56, v54, vcc
	v_lshl_add_u64 v[72:73], v[70:71], 0, v[68:69]
	global_load_dword v199, v[72:73], off
	v_add_u32_e32 v66, 34, v50
	v_cmp_gt_u32_e32 vcc, s77, v66
	v_lshlrev_b32_e32 v70, 12, v66
	v_add_u32_e32 v70, v70, v51
	v_cndmask_b32_e32 v68, v55, v53, vcc
	v_cndmask_b32_e32 v69, v56, v54, vcc
	v_lshl_add_u64 v[72:73], v[70:71], 0, v[68:69]
	global_load_dword v200, v[72:73], off
	v_add_u32_e32 v66, 35, v50
	v_cmp_gt_u32_e32 vcc, s77, v66
	v_lshlrev_b32_e32 v70, 12, v66
	v_add_u32_e32 v70, v70, v51
	v_cndmask_b32_e32 v68, v55, v53, vcc
	v_cndmask_b32_e32 v69, v56, v54, vcc
	v_lshl_add_u64 v[72:73], v[70:71], 0, v[68:69]
	global_load_dword v201, v[72:73], off
	v_add_u32_e32 v66, 32, v50
	v_cmp_gt_u32_e32 vcc, s77, v66
	v_lshlrev_b32_e32 v70, 12, v66
	v_add_u32_e32 v70, v70, v52
	v_cndmask_b32_e32 v68, v55, v53, vcc
	v_cndmask_b32_e32 v69, v56, v54, vcc
	v_lshl_add_u64 v[72:73], v[70:71], 0, v[68:69]
	global_load_dword v202, v[72:73], off
	v_add_u32_e32 v66, 33, v50
	v_cmp_gt_u32_e32 vcc, s77, v66
	v_lshlrev_b32_e32 v70, 12, v66
	v_add_u32_e32 v70, v70, v52
	v_cndmask_b32_e32 v68, v55, v53, vcc
	v_cndmask_b32_e32 v69, v56, v54, vcc
	v_lshl_add_u64 v[72:73], v[70:71], 0, v[68:69]
	global_load_dword v203, v[72:73], off
	v_add_u32_e32 v66, 34, v50
	v_cmp_gt_u32_e32 vcc, s77, v66
	v_lshlrev_b32_e32 v70, 12, v66
	v_add_u32_e32 v70, v70, v52
	v_cndmask_b32_e32 v68, v55, v53, vcc
	v_cndmask_b32_e32 v69, v56, v54, vcc
	v_lshl_add_u64 v[72:73], v[70:71], 0, v[68:69]
	global_load_dword v204, v[72:73], off
	v_add_u32_e32 v66, 35, v50
	v_cmp_gt_u32_e32 vcc, s77, v66
	v_lshlrev_b32_e32 v70, 12, v66
	v_add_u32_e32 v70, v70, v52
	v_cndmask_b32_e32 v68, v55, v53, vcc
	v_cndmask_b32_e32 v69, v56, v54, vcc
	v_lshl_add_u64 v[72:73], v[70:71], 0, v[68:69]
	global_load_dword v205, v[72:73], off
	v_add_u32_e32 v66, 48, v50
	v_cmp_gt_u32_e32 vcc, s77, v66
	v_lshlrev_b32_e32 v70, 12, v66
	v_add_u32_e32 v70, v70, v51
	v_cndmask_b32_e32 v68, v55, v53, vcc
	v_cndmask_b32_e32 v69, v56, v54, vcc
	v_lshl_add_u64 v[72:73], v[70:71], 0, v[68:69]
	global_load_dword v206, v[72:73], off
	v_add_u32_e32 v66, 49, v50
	v_cmp_gt_u32_e32 vcc, s77, v66
	v_lshlrev_b32_e32 v70, 12, v66
	v_add_u32_e32 v70, v70, v51
	v_cndmask_b32_e32 v68, v55, v53, vcc
	v_cndmask_b32_e32 v69, v56, v54, vcc
	v_lshl_add_u64 v[72:73], v[70:71], 0, v[68:69]
	global_load_dword v207, v[72:73], off
	v_add_u32_e32 v66, 50, v50
	v_cmp_gt_u32_e32 vcc, s77, v66
	v_lshlrev_b32_e32 v70, 12, v66
	v_add_u32_e32 v70, v70, v51
	v_cndmask_b32_e32 v68, v55, v53, vcc
	v_cndmask_b32_e32 v69, v56, v54, vcc
	v_lshl_add_u64 v[72:73], v[70:71], 0, v[68:69]
	global_load_dword v208, v[72:73], off
	v_add_u32_e32 v66, 51, v50
	v_cmp_gt_u32_e32 vcc, s77, v66
	v_lshlrev_b32_e32 v70, 12, v66
	v_add_u32_e32 v70, v70, v51
	v_cndmask_b32_e32 v68, v55, v53, vcc
	v_cndmask_b32_e32 v69, v56, v54, vcc
	v_lshl_add_u64 v[72:73], v[70:71], 0, v[68:69]
	global_load_dword v209, v[72:73], off
	v_add_u32_e32 v66, 48, v50
	v_cmp_gt_u32_e32 vcc, s77, v66
	v_lshlrev_b32_e32 v70, 12, v66
	v_add_u32_e32 v70, v70, v52
	v_cndmask_b32_e32 v68, v55, v53, vcc
	v_cndmask_b32_e32 v69, v56, v54, vcc
	v_lshl_add_u64 v[72:73], v[70:71], 0, v[68:69]
	global_load_dword v210, v[72:73], off
	v_add_u32_e32 v66, 49, v50
	v_cmp_gt_u32_e32 vcc, s77, v66
	v_lshlrev_b32_e32 v70, 12, v66
	v_add_u32_e32 v70, v70, v52
	v_cndmask_b32_e32 v68, v55, v53, vcc
	v_cndmask_b32_e32 v69, v56, v54, vcc
	v_lshl_add_u64 v[72:73], v[70:71], 0, v[68:69]
	global_load_dword v211, v[72:73], off
	v_add_u32_e32 v66, 50, v50
	v_cmp_gt_u32_e32 vcc, s77, v66
	v_lshlrev_b32_e32 v70, 12, v66
	v_add_u32_e32 v70, v70, v52
	v_cndmask_b32_e32 v68, v55, v53, vcc
	v_cndmask_b32_e32 v69, v56, v54, vcc
	v_lshl_add_u64 v[72:73], v[70:71], 0, v[68:69]
	global_load_dword v212, v[72:73], off
	v_add_u32_e32 v66, 51, v50
	v_cmp_gt_u32_e32 vcc, s77, v66
	v_lshlrev_b32_e32 v70, 12, v66
	v_add_u32_e32 v70, v70, v52
	v_cndmask_b32_e32 v68, v55, v53, vcc
	v_cndmask_b32_e32 v69, v56, v54, vcc
	v_lshl_add_u64 v[72:73], v[70:71], 0, v[68:69]
	global_load_dword v213, v[72:73], off
	v_add_u32_e32 v66, 64, v50
	v_cmp_gt_u32_e32 vcc, s77, v66
	v_lshlrev_b32_e32 v70, 12, v66
	v_add_u32_e32 v70, v70, v51
	v_cndmask_b32_e32 v68, v55, v53, vcc
	v_cndmask_b32_e32 v69, v56, v54, vcc
	v_lshl_add_u64 v[72:73], v[70:71], 0, v[68:69]
	global_load_dword v214, v[72:73], off
	v_add_u32_e32 v66, 65, v50
	v_cmp_gt_u32_e32 vcc, s77, v66
	v_lshlrev_b32_e32 v70, 12, v66
	v_add_u32_e32 v70, v70, v51
	v_cndmask_b32_e32 v68, v55, v53, vcc
	v_cndmask_b32_e32 v69, v56, v54, vcc
	v_lshl_add_u64 v[72:73], v[70:71], 0, v[68:69]
	global_load_dword v215, v[72:73], off
	v_add_u32_e32 v66, 66, v50
	v_cmp_gt_u32_e32 vcc, s77, v66
	v_lshlrev_b32_e32 v70, 12, v66
	v_add_u32_e32 v70, v70, v51
	v_cndmask_b32_e32 v68, v55, v53, vcc
	v_cndmask_b32_e32 v69, v56, v54, vcc
	v_lshl_add_u64 v[72:73], v[70:71], 0, v[68:69]
	global_load_dword v216, v[72:73], off
	v_add_u32_e32 v66, 67, v50
	v_cmp_gt_u32_e32 vcc, s77, v66
	v_lshlrev_b32_e32 v70, 12, v66
	v_add_u32_e32 v70, v70, v51
	v_cndmask_b32_e32 v68, v55, v53, vcc
	v_cndmask_b32_e32 v69, v56, v54, vcc
	v_lshl_add_u64 v[72:73], v[70:71], 0, v[68:69]
	global_load_dword v217, v[72:73], off
	v_add_u32_e32 v66, 64, v50
	v_cmp_gt_u32_e32 vcc, s77, v66
	v_lshlrev_b32_e32 v70, 12, v66
	v_add_u32_e32 v70, v70, v52
	v_cndmask_b32_e32 v68, v55, v53, vcc
	v_cndmask_b32_e32 v69, v56, v54, vcc
	v_lshl_add_u64 v[72:73], v[70:71], 0, v[68:69]
	global_load_dword v218, v[72:73], off
	v_add_u32_e32 v66, 65, v50
	v_cmp_gt_u32_e32 vcc, s77, v66
	v_lshlrev_b32_e32 v70, 12, v66
	v_add_u32_e32 v70, v70, v52
	v_cndmask_b32_e32 v68, v55, v53, vcc
	v_cndmask_b32_e32 v69, v56, v54, vcc
	v_lshl_add_u64 v[72:73], v[70:71], 0, v[68:69]
	global_load_dword v219, v[72:73], off
	v_add_u32_e32 v66, 66, v50
	v_cmp_gt_u32_e32 vcc, s77, v66
	v_lshlrev_b32_e32 v70, 12, v66
	v_add_u32_e32 v70, v70, v52
	v_cndmask_b32_e32 v68, v55, v53, vcc
	v_cndmask_b32_e32 v69, v56, v54, vcc
	v_lshl_add_u64 v[72:73], v[70:71], 0, v[68:69]
	global_load_dword v220, v[72:73], off
	v_add_u32_e32 v66, 67, v50
	v_cmp_gt_u32_e32 vcc, s77, v66
	v_lshlrev_b32_e32 v70, 12, v66
	v_add_u32_e32 v70, v70, v52
	v_cndmask_b32_e32 v68, v55, v53, vcc
	v_cndmask_b32_e32 v69, v56, v54, vcc
	v_lshl_add_u64 v[72:73], v[70:71], 0, v[68:69]
	global_load_dword v221, v[72:73], off
	v_add_u32_e32 v66, 80, v50
	v_cmp_gt_u32_e32 vcc, s77, v66
	v_lshlrev_b32_e32 v70, 12, v66
	v_add_u32_e32 v70, v70, v51
	v_cndmask_b32_e32 v68, v55, v53, vcc
	v_cndmask_b32_e32 v69, v56, v54, vcc
	v_lshl_add_u64 v[72:73], v[70:71], 0, v[68:69]
	global_load_dword v222, v[72:73], off
	v_add_u32_e32 v66, 81, v50
	v_cmp_gt_u32_e32 vcc, s77, v66
	v_lshlrev_b32_e32 v70, 12, v66
	v_add_u32_e32 v70, v70, v51
	v_cndmask_b32_e32 v68, v55, v53, vcc
	v_cndmask_b32_e32 v69, v56, v54, vcc
	v_lshl_add_u64 v[72:73], v[70:71], 0, v[68:69]
	global_load_dword v223, v[72:73], off
	v_add_u32_e32 v66, 82, v50
	v_cmp_gt_u32_e32 vcc, s77, v66
	v_lshlrev_b32_e32 v70, 12, v66
	v_add_u32_e32 v70, v70, v51
	v_cndmask_b32_e32 v68, v55, v53, vcc
	v_cndmask_b32_e32 v69, v56, v54, vcc
	v_lshl_add_u64 v[72:73], v[70:71], 0, v[68:69]
	global_load_dword v224, v[72:73], off
	v_add_u32_e32 v66, 83, v50
	v_cmp_gt_u32_e32 vcc, s77, v66
	v_lshlrev_b32_e32 v70, 12, v66
	v_add_u32_e32 v70, v70, v51
	v_cndmask_b32_e32 v68, v55, v53, vcc
	v_cndmask_b32_e32 v69, v56, v54, vcc
	v_lshl_add_u64 v[72:73], v[70:71], 0, v[68:69]
	global_load_dword v225, v[72:73], off
	v_add_u32_e32 v66, 80, v50
	v_cmp_gt_u32_e32 vcc, s77, v66
	v_lshlrev_b32_e32 v70, 12, v66
	v_add_u32_e32 v70, v70, v52
	v_cndmask_b32_e32 v68, v55, v53, vcc
	v_cndmask_b32_e32 v69, v56, v54, vcc
	v_lshl_add_u64 v[72:73], v[70:71], 0, v[68:69]
	global_load_dword v226, v[72:73], off
	v_add_u32_e32 v66, 81, v50
	v_cmp_gt_u32_e32 vcc, s77, v66
	v_lshlrev_b32_e32 v70, 12, v66
	v_add_u32_e32 v70, v70, v52
	v_cndmask_b32_e32 v68, v55, v53, vcc
	v_cndmask_b32_e32 v69, v56, v54, vcc
	v_lshl_add_u64 v[72:73], v[70:71], 0, v[68:69]
	global_load_dword v227, v[72:73], off
	v_add_u32_e32 v66, 82, v50
	v_cmp_gt_u32_e32 vcc, s77, v66
	v_lshlrev_b32_e32 v70, 12, v66
	v_add_u32_e32 v70, v70, v52
	v_cndmask_b32_e32 v68, v55, v53, vcc
	v_cndmask_b32_e32 v69, v56, v54, vcc
	v_lshl_add_u64 v[72:73], v[70:71], 0, v[68:69]
	global_load_dword v228, v[72:73], off
	v_add_u32_e32 v66, 83, v50
	v_cmp_gt_u32_e32 vcc, s77, v66
	v_lshlrev_b32_e32 v70, 12, v66
	v_add_u32_e32 v70, v70, v52
	v_cndmask_b32_e32 v68, v55, v53, vcc
	v_cndmask_b32_e32 v69, v56, v54, vcc
	v_lshl_add_u64 v[72:73], v[70:71], 0, v[68:69]
	global_load_dword v229, v[72:73], off
	s_waitcnt vmcnt(48)
	v_mul_f32_e32 v60, s6, v60
	v_mul_f32_e32 v61, s6, v61
	v_mul_f32_e32 v62, s6, v62
	v_mul_f32_e32 v63, s6, v63
	v_mul_f32_e32 v64, s6, v64
	v_mul_f32_e32 v65, s6, v65
	s_movk_i32 s7, 0x1400
	v_mov_b32_e32 v66, v50
	v_cmp_gt_u32_e32 vcc, s7, v66
	v_lshlrev_b32_e32 v70, 12, v66
	v_add_u32_e32 v70, v70, v51
	v_cndmask_b32_e32 v75, v62, v61, vcc
	v_cmp_gt_u32_e32 vcc, s77, v66
	s_waitcnt vmcnt(47)
	s_nop 1
	v_cndmask_b32_e32 v74, v75, v60, vcc
	v_fmac_f32_e32 v182, v74, v0
	global_store_dword v70, v182, s[12:13]
	v_add_u32_e32 v66, 1, v50
	v_cmp_gt_u32_e32 vcc, s7, v66
	v_lshlrev_b32_e32 v70, 12, v66
	v_add_u32_e32 v70, v70, v51
	v_cndmask_b32_e32 v75, v62, v61, vcc
	v_cmp_gt_u32_e32 vcc, s77, v66
	s_waitcnt vmcnt(47)
	s_nop 1
	v_cndmask_b32_e32 v74, v75, v60, vcc
	v_fmac_f32_e32 v183, v74, v1
	global_store_dword v70, v183, s[12:13]
	v_add_u32_e32 v66, 2, v50
	v_cmp_gt_u32_e32 vcc, s7, v66
	v_lshlrev_b32_e32 v70, 12, v66
	v_add_u32_e32 v70, v70, v51
	v_cndmask_b32_e32 v75, v62, v61, vcc
	v_cmp_gt_u32_e32 vcc, s77, v66
	s_waitcnt vmcnt(47)
	s_nop 1
	v_cndmask_b32_e32 v74, v75, v60, vcc
	v_fmac_f32_e32 v184, v74, v2
	global_store_dword v70, v184, s[12:13]
	v_add_u32_e32 v66, 3, v50
	v_cmp_gt_u32_e32 vcc, s7, v66
	v_lshlrev_b32_e32 v70, 12, v66
	v_add_u32_e32 v70, v70, v51
	v_cndmask_b32_e32 v75, v62, v61, vcc
	v_cmp_gt_u32_e32 vcc, s77, v66
	s_waitcnt vmcnt(47)
	s_nop 1
	v_cndmask_b32_e32 v74, v75, v60, vcc
	v_fmac_f32_e32 v185, v74, v3
	global_store_dword v70, v185, s[12:13]
	v_mov_b32_e32 v66, v50
	v_cmp_gt_u32_e32 vcc, s7, v66
	v_lshlrev_b32_e32 v70, 12, v66
	v_add_u32_e32 v70, v70, v52
	v_cndmask_b32_e32 v75, v65, v64, vcc
	v_cmp_gt_u32_e32 vcc, s77, v66
	s_waitcnt vmcnt(47)
	s_nop 1
	v_cndmask_b32_e32 v74, v75, v63, vcc
	v_fmac_f32_e32 v186, v74, v4
	global_store_dword v70, v186, s[12:13]
	v_add_u32_e32 v66, 1, v50
	v_cmp_gt_u32_e32 vcc, s7, v66
	v_lshlrev_b32_e32 v70, 12, v66
	v_add_u32_e32 v70, v70, v52
	v_cndmask_b32_e32 v75, v65, v64, vcc
	v_cmp_gt_u32_e32 vcc, s77, v66
	s_waitcnt vmcnt(47)
	s_nop 1
	v_cndmask_b32_e32 v74, v75, v63, vcc
	v_fmac_f32_e32 v187, v74, v5
	global_store_dword v70, v187, s[12:13]
	v_add_u32_e32 v66, 2, v50
	v_cmp_gt_u32_e32 vcc, s7, v66
	v_lshlrev_b32_e32 v70, 12, v66
	v_add_u32_e32 v70, v70, v52
	v_cndmask_b32_e32 v75, v65, v64, vcc
	v_cmp_gt_u32_e32 vcc, s77, v66
	s_waitcnt vmcnt(47)
	s_nop 1
	v_cndmask_b32_e32 v74, v75, v63, vcc
	v_fmac_f32_e32 v188, v74, v6
	global_store_dword v70, v188, s[12:13]
	v_add_u32_e32 v66, 3, v50
	v_cmp_gt_u32_e32 vcc, s7, v66
	v_lshlrev_b32_e32 v70, 12, v66
	v_add_u32_e32 v70, v70, v52
	v_cndmask_b32_e32 v75, v65, v64, vcc
	v_cmp_gt_u32_e32 vcc, s77, v66
	s_waitcnt vmcnt(47)
	s_nop 1
	v_cndmask_b32_e32 v74, v75, v63, vcc
	v_fmac_f32_e32 v189, v74, v7
	global_store_dword v70, v189, s[12:13]
	v_add_u32_e32 v66, 16, v50
	v_cmp_gt_u32_e32 vcc, s7, v66
	v_lshlrev_b32_e32 v70, 12, v66
	v_add_u32_e32 v70, v70, v51
	v_cndmask_b32_e32 v75, v62, v61, vcc
	v_cmp_gt_u32_e32 vcc, s77, v66
	s_waitcnt vmcnt(47)
	s_nop 1
	v_cndmask_b32_e32 v74, v75, v60, vcc
	v_fmac_f32_e32 v190, v74, v8
	global_store_dword v70, v190, s[12:13]
	v_add_u32_e32 v66, 17, v50
	v_cmp_gt_u32_e32 vcc, s7, v66
	v_lshlrev_b32_e32 v70, 12, v66
	v_add_u32_e32 v70, v70, v51
	v_cndmask_b32_e32 v75, v62, v61, vcc
	v_cmp_gt_u32_e32 vcc, s77, v66
	s_waitcnt vmcnt(47)
	s_nop 1
	v_cndmask_b32_e32 v74, v75, v60, vcc
	v_fmac_f32_e32 v191, v74, v9
	global_store_dword v70, v191, s[12:13]
	v_add_u32_e32 v66, 18, v50
	v_cmp_gt_u32_e32 vcc, s7, v66
	v_lshlrev_b32_e32 v70, 12, v66
	v_add_u32_e32 v70, v70, v51
	v_cndmask_b32_e32 v75, v62, v61, vcc
	v_cmp_gt_u32_e32 vcc, s77, v66
	s_waitcnt vmcnt(47)
	s_nop 1
	v_cndmask_b32_e32 v74, v75, v60, vcc
	v_fmac_f32_e32 v192, v74, v10
	global_store_dword v70, v192, s[12:13]
	v_add_u32_e32 v66, 19, v50
	v_cmp_gt_u32_e32 vcc, s7, v66
	v_lshlrev_b32_e32 v70, 12, v66
	v_add_u32_e32 v70, v70, v51
	v_cndmask_b32_e32 v75, v62, v61, vcc
	v_cmp_gt_u32_e32 vcc, s77, v66
	s_waitcnt vmcnt(47)
	s_nop 1
	v_cndmask_b32_e32 v74, v75, v60, vcc
	v_fmac_f32_e32 v193, v74, v11
	global_store_dword v70, v193, s[12:13]
	v_add_u32_e32 v66, 16, v50
	v_cmp_gt_u32_e32 vcc, s7, v66
	v_lshlrev_b32_e32 v70, 12, v66
	v_add_u32_e32 v70, v70, v52
	v_cndmask_b32_e32 v75, v65, v64, vcc
	v_cmp_gt_u32_e32 vcc, s77, v66
	s_waitcnt vmcnt(47)
	s_nop 1
	v_cndmask_b32_e32 v74, v75, v63, vcc
	v_fmac_f32_e32 v194, v74, v12
	global_store_dword v70, v194, s[12:13]
	v_add_u32_e32 v66, 17, v50
	v_cmp_gt_u32_e32 vcc, s7, v66
	v_lshlrev_b32_e32 v70, 12, v66
	v_add_u32_e32 v70, v70, v52
	v_cndmask_b32_e32 v75, v65, v64, vcc
	v_cmp_gt_u32_e32 vcc, s77, v66
	s_waitcnt vmcnt(47)
	s_nop 1
	v_cndmask_b32_e32 v74, v75, v63, vcc
	v_fmac_f32_e32 v195, v74, v13
	global_store_dword v70, v195, s[12:13]
	v_add_u32_e32 v66, 18, v50
	v_cmp_gt_u32_e32 vcc, s7, v66
	v_lshlrev_b32_e32 v70, 12, v66
	v_add_u32_e32 v70, v70, v52
	v_cndmask_b32_e32 v75, v65, v64, vcc
	v_cmp_gt_u32_e32 vcc, s77, v66
	s_waitcnt vmcnt(47)
	s_nop 1
	v_cndmask_b32_e32 v74, v75, v63, vcc
	v_fmac_f32_e32 v196, v74, v14
	global_store_dword v70, v196, s[12:13]
	v_add_u32_e32 v66, 19, v50
	v_cmp_gt_u32_e32 vcc, s7, v66
	v_lshlrev_b32_e32 v70, 12, v66
	v_add_u32_e32 v70, v70, v52
	v_cndmask_b32_e32 v75, v65, v64, vcc
	v_cmp_gt_u32_e32 vcc, s77, v66
	s_waitcnt vmcnt(47)
	s_nop 1
	v_cndmask_b32_e32 v74, v75, v63, vcc
	v_fmac_f32_e32 v197, v74, v15
	global_store_dword v70, v197, s[12:13]
	v_add_u32_e32 v66, 32, v50
	v_cmp_gt_u32_e32 vcc, s7, v66
	v_lshlrev_b32_e32 v70, 12, v66
	v_add_u32_e32 v70, v70, v51
	v_cndmask_b32_e32 v75, v62, v61, vcc
	v_cmp_gt_u32_e32 vcc, s77, v66
	s_waitcnt vmcnt(47)
	s_nop 1
	v_cndmask_b32_e32 v74, v75, v60, vcc
	v_fmac_f32_e32 v198, v74, v16
	global_store_dword v70, v198, s[12:13]
	v_add_u32_e32 v66, 33, v50
	v_cmp_gt_u32_e32 vcc, s7, v66
	v_lshlrev_b32_e32 v70, 12, v66
	v_add_u32_e32 v70, v70, v51
	v_cndmask_b32_e32 v75, v62, v61, vcc
	v_cmp_gt_u32_e32 vcc, s77, v66
	s_waitcnt vmcnt(47)
	s_nop 1
	v_cndmask_b32_e32 v74, v75, v60, vcc
	v_fmac_f32_e32 v199, v74, v17
	global_store_dword v70, v199, s[12:13]
	v_add_u32_e32 v66, 34, v50
	v_cmp_gt_u32_e32 vcc, s7, v66
	v_lshlrev_b32_e32 v70, 12, v66
	v_add_u32_e32 v70, v70, v51
	v_cndmask_b32_e32 v75, v62, v61, vcc
	v_cmp_gt_u32_e32 vcc, s77, v66
	s_waitcnt vmcnt(47)
	s_nop 1
	v_cndmask_b32_e32 v74, v75, v60, vcc
	v_fmac_f32_e32 v200, v74, v18
	global_store_dword v70, v200, s[12:13]
	v_add_u32_e32 v66, 35, v50
	v_cmp_gt_u32_e32 vcc, s7, v66
	v_lshlrev_b32_e32 v70, 12, v66
	v_add_u32_e32 v70, v70, v51
	v_cndmask_b32_e32 v75, v62, v61, vcc
	v_cmp_gt_u32_e32 vcc, s77, v66
	s_waitcnt vmcnt(47)
	s_nop 1
	v_cndmask_b32_e32 v74, v75, v60, vcc
	v_fmac_f32_e32 v201, v74, v19
	global_store_dword v70, v201, s[12:13]
	v_add_u32_e32 v66, 32, v50
	v_cmp_gt_u32_e32 vcc, s7, v66
	v_lshlrev_b32_e32 v70, 12, v66
	v_add_u32_e32 v70, v70, v52
	v_cndmask_b32_e32 v75, v65, v64, vcc
	v_cmp_gt_u32_e32 vcc, s77, v66
	s_waitcnt vmcnt(47)
	s_nop 1
	v_cndmask_b32_e32 v74, v75, v63, vcc
	v_fmac_f32_e32 v202, v74, v20
	global_store_dword v70, v202, s[12:13]
	v_add_u32_e32 v66, 33, v50
	v_cmp_gt_u32_e32 vcc, s7, v66
	v_lshlrev_b32_e32 v70, 12, v66
	v_add_u32_e32 v70, v70, v52
	v_cndmask_b32_e32 v75, v65, v64, vcc
	v_cmp_gt_u32_e32 vcc, s77, v66
	s_waitcnt vmcnt(47)
	s_nop 1
	v_cndmask_b32_e32 v74, v75, v63, vcc
	v_fmac_f32_e32 v203, v74, v21
	global_store_dword v70, v203, s[12:13]
	v_add_u32_e32 v66, 34, v50
	v_cmp_gt_u32_e32 vcc, s7, v66
	v_lshlrev_b32_e32 v70, 12, v66
	v_add_u32_e32 v70, v70, v52
	v_cndmask_b32_e32 v75, v65, v64, vcc
	v_cmp_gt_u32_e32 vcc, s77, v66
	s_waitcnt vmcnt(47)
	s_nop 1
	v_cndmask_b32_e32 v74, v75, v63, vcc
	v_fmac_f32_e32 v204, v74, v22
	global_store_dword v70, v204, s[12:13]
	v_add_u32_e32 v66, 35, v50
	v_cmp_gt_u32_e32 vcc, s7, v66
	v_lshlrev_b32_e32 v70, 12, v66
	v_add_u32_e32 v70, v70, v52
	v_cndmask_b32_e32 v75, v65, v64, vcc
	v_cmp_gt_u32_e32 vcc, s77, v66
	s_waitcnt vmcnt(47)
	s_nop 1
	v_cndmask_b32_e32 v74, v75, v63, vcc
	v_fmac_f32_e32 v205, v74, v23
	global_store_dword v70, v205, s[12:13]
	v_add_u32_e32 v66, 48, v50
	v_cmp_gt_u32_e32 vcc, s7, v66
	v_lshlrev_b32_e32 v70, 12, v66
	v_add_u32_e32 v70, v70, v51
	v_cndmask_b32_e32 v75, v62, v61, vcc
	v_cmp_gt_u32_e32 vcc, s77, v66
	s_waitcnt vmcnt(47)
	s_nop 1
	v_cndmask_b32_e32 v74, v75, v60, vcc
	v_fmac_f32_e32 v206, v74, v24
	global_store_dword v70, v206, s[12:13]
	v_add_u32_e32 v66, 49, v50
	v_cmp_gt_u32_e32 vcc, s7, v66
	v_lshlrev_b32_e32 v70, 12, v66
	v_add_u32_e32 v70, v70, v51
	v_cndmask_b32_e32 v75, v62, v61, vcc
	v_cmp_gt_u32_e32 vcc, s77, v66
	s_waitcnt vmcnt(47)
	s_nop 1
	v_cndmask_b32_e32 v74, v75, v60, vcc
	v_fmac_f32_e32 v207, v74, v25
	global_store_dword v70, v207, s[12:13]
	v_add_u32_e32 v66, 50, v50
	v_cmp_gt_u32_e32 vcc, s7, v66
	v_lshlrev_b32_e32 v70, 12, v66
	v_add_u32_e32 v70, v70, v51
	v_cndmask_b32_e32 v75, v62, v61, vcc
	v_cmp_gt_u32_e32 vcc, s77, v66
	s_waitcnt vmcnt(47)
	s_nop 1
	v_cndmask_b32_e32 v74, v75, v60, vcc
	v_fmac_f32_e32 v208, v74, v26
	global_store_dword v70, v208, s[12:13]
	v_add_u32_e32 v66, 51, v50
	v_cmp_gt_u32_e32 vcc, s7, v66
	v_lshlrev_b32_e32 v70, 12, v66
	v_add_u32_e32 v70, v70, v51
	v_cndmask_b32_e32 v75, v62, v61, vcc
	v_cmp_gt_u32_e32 vcc, s77, v66
	s_waitcnt vmcnt(47)
	s_nop 1
	v_cndmask_b32_e32 v74, v75, v60, vcc
	v_fmac_f32_e32 v209, v74, v27
	global_store_dword v70, v209, s[12:13]
	v_add_u32_e32 v66, 48, v50
	v_cmp_gt_u32_e32 vcc, s7, v66
	v_lshlrev_b32_e32 v70, 12, v66
	v_add_u32_e32 v70, v70, v52
	v_cndmask_b32_e32 v75, v65, v64, vcc
	v_cmp_gt_u32_e32 vcc, s77, v66
	s_waitcnt vmcnt(47)
	s_nop 1
	v_cndmask_b32_e32 v74, v75, v63, vcc
	v_fmac_f32_e32 v210, v74, v28
	global_store_dword v70, v210, s[12:13]
	v_add_u32_e32 v66, 49, v50
	v_cmp_gt_u32_e32 vcc, s7, v66
	v_lshlrev_b32_e32 v70, 12, v66
	v_add_u32_e32 v70, v70, v52
	v_cndmask_b32_e32 v75, v65, v64, vcc
	v_cmp_gt_u32_e32 vcc, s77, v66
	s_waitcnt vmcnt(47)
	s_nop 1
	v_cndmask_b32_e32 v74, v75, v63, vcc
	v_fmac_f32_e32 v211, v74, v29
	global_store_dword v70, v211, s[12:13]
	v_add_u32_e32 v66, 50, v50
	v_cmp_gt_u32_e32 vcc, s7, v66
	v_lshlrev_b32_e32 v70, 12, v66
	v_add_u32_e32 v70, v70, v52
	v_cndmask_b32_e32 v75, v65, v64, vcc
	v_cmp_gt_u32_e32 vcc, s77, v66
	s_waitcnt vmcnt(47)
	s_nop 1
	v_cndmask_b32_e32 v74, v75, v63, vcc
	v_fmac_f32_e32 v212, v74, v30
	global_store_dword v70, v212, s[12:13]
	v_add_u32_e32 v66, 51, v50
	v_cmp_gt_u32_e32 vcc, s7, v66
	v_lshlrev_b32_e32 v70, 12, v66
	v_add_u32_e32 v70, v70, v52
	v_cndmask_b32_e32 v75, v65, v64, vcc
	v_cmp_gt_u32_e32 vcc, s77, v66
	s_waitcnt vmcnt(47)
	s_nop 1
	v_cndmask_b32_e32 v74, v75, v63, vcc
	v_fmac_f32_e32 v213, v74, v31
	global_store_dword v70, v213, s[12:13]
	v_add_u32_e32 v66, 64, v50
	v_cmp_gt_u32_e32 vcc, s7, v66
	v_lshlrev_b32_e32 v70, 12, v66
	v_add_u32_e32 v70, v70, v51
	v_cndmask_b32_e32 v75, v62, v61, vcc
	v_cmp_gt_u32_e32 vcc, s77, v66
	s_waitcnt vmcnt(47)
	s_nop 1
	v_cndmask_b32_e32 v74, v75, v60, vcc
	v_fmac_f32_e32 v214, v74, v32
	global_store_dword v70, v214, s[12:13]
	v_add_u32_e32 v66, 65, v50
	v_cmp_gt_u32_e32 vcc, s7, v66
	v_lshlrev_b32_e32 v70, 12, v66
	v_add_u32_e32 v70, v70, v51
	v_cndmask_b32_e32 v75, v62, v61, vcc
	v_cmp_gt_u32_e32 vcc, s77, v66
	s_waitcnt vmcnt(47)
	s_nop 1
	v_cndmask_b32_e32 v74, v75, v60, vcc
	v_fmac_f32_e32 v215, v74, v33
	global_store_dword v70, v215, s[12:13]
	v_add_u32_e32 v66, 66, v50
	v_cmp_gt_u32_e32 vcc, s7, v66
	v_lshlrev_b32_e32 v70, 12, v66
	v_add_u32_e32 v70, v70, v51
	v_cndmask_b32_e32 v75, v62, v61, vcc
	v_cmp_gt_u32_e32 vcc, s77, v66
	s_waitcnt vmcnt(47)
	s_nop 1
	v_cndmask_b32_e32 v74, v75, v60, vcc
	v_fmac_f32_e32 v216, v74, v34
	global_store_dword v70, v216, s[12:13]
	v_add_u32_e32 v66, 67, v50
	v_cmp_gt_u32_e32 vcc, s7, v66
	v_lshlrev_b32_e32 v70, 12, v66
	v_add_u32_e32 v70, v70, v51
	v_cndmask_b32_e32 v75, v62, v61, vcc
	v_cmp_gt_u32_e32 vcc, s77, v66
	s_waitcnt vmcnt(47)
	s_nop 1
	v_cndmask_b32_e32 v74, v75, v60, vcc
	v_fmac_f32_e32 v217, v74, v35
	global_store_dword v70, v217, s[12:13]
	v_add_u32_e32 v66, 64, v50
	v_cmp_gt_u32_e32 vcc, s7, v66
	v_lshlrev_b32_e32 v70, 12, v66
	v_add_u32_e32 v70, v70, v52
	v_cndmask_b32_e32 v75, v65, v64, vcc
	v_cmp_gt_u32_e32 vcc, s77, v66
	s_waitcnt vmcnt(47)
	s_nop 1
	v_cndmask_b32_e32 v74, v75, v63, vcc
	v_fmac_f32_e32 v218, v74, v36
	global_store_dword v70, v218, s[12:13]
	v_add_u32_e32 v66, 65, v50
	v_cmp_gt_u32_e32 vcc, s7, v66
	v_lshlrev_b32_e32 v70, 12, v66
	v_add_u32_e32 v70, v70, v52
	v_cndmask_b32_e32 v75, v65, v64, vcc
	v_cmp_gt_u32_e32 vcc, s77, v66
	s_waitcnt vmcnt(47)
	s_nop 1
	v_cndmask_b32_e32 v74, v75, v63, vcc
	v_fmac_f32_e32 v219, v74, v37
	global_store_dword v70, v219, s[12:13]
	v_add_u32_e32 v66, 66, v50
	v_cmp_gt_u32_e32 vcc, s7, v66
	v_lshlrev_b32_e32 v70, 12, v66
	v_add_u32_e32 v70, v70, v52
	v_cndmask_b32_e32 v75, v65, v64, vcc
	v_cmp_gt_u32_e32 vcc, s77, v66
	s_waitcnt vmcnt(47)
	s_nop 1
	v_cndmask_b32_e32 v74, v75, v63, vcc
	v_fmac_f32_e32 v220, v74, v38
	global_store_dword v70, v220, s[12:13]
	v_add_u32_e32 v66, 67, v50
	v_cmp_gt_u32_e32 vcc, s7, v66
	v_lshlrev_b32_e32 v70, 12, v66
	v_add_u32_e32 v70, v70, v52
	v_cndmask_b32_e32 v75, v65, v64, vcc
	v_cmp_gt_u32_e32 vcc, s77, v66
	s_waitcnt vmcnt(47)
	s_nop 1
	v_cndmask_b32_e32 v74, v75, v63, vcc
	v_fmac_f32_e32 v221, v74, v39
	global_store_dword v70, v221, s[12:13]
	v_add_u32_e32 v66, 80, v50
	v_cmp_gt_u32_e32 vcc, s7, v66
	v_lshlrev_b32_e32 v70, 12, v66
	v_add_u32_e32 v70, v70, v51
	v_cndmask_b32_e32 v75, v62, v61, vcc
	v_cmp_gt_u32_e32 vcc, s77, v66
	s_waitcnt vmcnt(47)
	s_nop 1
	v_cndmask_b32_e32 v74, v75, v60, vcc
	v_fmac_f32_e32 v222, v74, v40
	global_store_dword v70, v222, s[12:13]
	v_add_u32_e32 v66, 81, v50
	v_cmp_gt_u32_e32 vcc, s7, v66
	v_lshlrev_b32_e32 v70, 12, v66
	v_add_u32_e32 v70, v70, v51
	v_cndmask_b32_e32 v75, v62, v61, vcc
	v_cmp_gt_u32_e32 vcc, s77, v66
	s_waitcnt vmcnt(47)
	s_nop 1
	v_cndmask_b32_e32 v74, v75, v60, vcc
	v_fmac_f32_e32 v223, v74, v41
	global_store_dword v70, v223, s[12:13]
	v_add_u32_e32 v66, 82, v50
	v_cmp_gt_u32_e32 vcc, s7, v66
	v_lshlrev_b32_e32 v70, 12, v66
	v_add_u32_e32 v70, v70, v51
	v_cndmask_b32_e32 v75, v62, v61, vcc
	v_cmp_gt_u32_e32 vcc, s77, v66
	s_waitcnt vmcnt(47)
	s_nop 1
	v_cndmask_b32_e32 v74, v75, v60, vcc
	v_fmac_f32_e32 v224, v74, v42
	global_store_dword v70, v224, s[12:13]
	v_add_u32_e32 v66, 83, v50
	v_cmp_gt_u32_e32 vcc, s7, v66
	v_lshlrev_b32_e32 v70, 12, v66
	v_add_u32_e32 v70, v70, v51
	v_cndmask_b32_e32 v75, v62, v61, vcc
	v_cmp_gt_u32_e32 vcc, s77, v66
	s_waitcnt vmcnt(47)
	s_nop 1
	v_cndmask_b32_e32 v74, v75, v60, vcc
	v_fmac_f32_e32 v225, v74, v43
	global_store_dword v70, v225, s[12:13]
	v_add_u32_e32 v66, 80, v50
	v_cmp_gt_u32_e32 vcc, s7, v66
	v_lshlrev_b32_e32 v70, 12, v66
	v_add_u32_e32 v70, v70, v52
	v_cndmask_b32_e32 v75, v65, v64, vcc
	v_cmp_gt_u32_e32 vcc, s77, v66
	s_waitcnt vmcnt(47)
	s_nop 1
	v_cndmask_b32_e32 v74, v75, v63, vcc
	v_fmac_f32_e32 v226, v74, v44
	global_store_dword v70, v226, s[12:13]
	v_add_u32_e32 v66, 81, v50
	v_cmp_gt_u32_e32 vcc, s7, v66
	v_lshlrev_b32_e32 v70, 12, v66
	v_add_u32_e32 v70, v70, v52
	v_cndmask_b32_e32 v75, v65, v64, vcc
	v_cmp_gt_u32_e32 vcc, s77, v66
	s_waitcnt vmcnt(47)
	s_nop 1
	v_cndmask_b32_e32 v74, v75, v63, vcc
	v_fmac_f32_e32 v227, v74, v45
	global_store_dword v70, v227, s[12:13]
	v_add_u32_e32 v66, 82, v50
	v_cmp_gt_u32_e32 vcc, s7, v66
	v_lshlrev_b32_e32 v70, 12, v66
	v_add_u32_e32 v70, v70, v52
	v_cndmask_b32_e32 v75, v65, v64, vcc
	v_cmp_gt_u32_e32 vcc, s77, v66
	s_waitcnt vmcnt(47)
	s_nop 1
	v_cndmask_b32_e32 v74, v75, v63, vcc
	v_fmac_f32_e32 v228, v74, v46
	global_store_dword v70, v228, s[12:13]
	v_add_u32_e32 v66, 83, v50
	v_cmp_gt_u32_e32 vcc, s7, v66
	v_lshlrev_b32_e32 v70, 12, v66
	v_add_u32_e32 v70, v70, v52
	v_cndmask_b32_e32 v75, v65, v64, vcc
	v_cmp_gt_u32_e32 vcc, s77, v66
	s_waitcnt vmcnt(47)
	s_nop 1
	v_cndmask_b32_e32 v74, v75, v63, vcc
	v_fmac_f32_e32 v229, v74, v47
	global_store_dword v70, v229, s[12:13]
	s_add_i32 s43, s43, s76
	s_cmpk_gt_i32 s43, 0x1ff
	s_cbranch_scc1 .LBB0_1331
.LBB0_1134:
	s_waitcnt vmcnt(7)
	v_mov_b32_e32 v18, v127
	s_ashr_i32 s0, s43, 31
	s_lshr_b32 s0, s0, 26
	v_ashrrev_i32_e32 v19, 6, v18
	s_waitcnt vmcnt(6)
	v_bfe_u32 v21, v18, 3, 3
	v_lshlrev_b32_e32 v22, 3, v19
	s_add_i32 s0, s43, s0
	v_or_b32_e32 v8, v22, v21
	v_lshrrev_b32_e32 v9, 30, v19
	s_ashr_i32 s7, s0, 6
	s_and_b32 s0, s0, 0x7ffffc0
	v_lshrrev_b32_e32 v23, 1, v8
	v_add_u32_e32 v9, v19, v9
	s_sub_i32 s4, s43, s0
	s_lshl_b32 s5, s7, 7
	v_xor_b32_e32 v4, v23, v18
	s_waitcnt vmcnt(5)
	v_ashrrev_i32_e32 v24, 2, v9
	s_mulk_i32 s4, 0x60
	v_and_b32_e32 v20, 63, v18
	v_readlane_b32 s10, v238, 6
	v_lshlrev_b32_e32 v4, 4, v4
	v_add_u32_e32 v12, 32, v8
	v_add_u32_e32 v14, 64, v8
	v_mul_i32_i24_e32 v9, 4, v24
	v_add_u32_e32 v16, s5, v8
	v_add_u32_e32 v0, s4, v8
	v_and_b32_e32 v124, 0x70, v4
	v_add_u32_e32 v4, s4, v12
	v_add_u32_e32 v6, s4, v14
	v_sub_u32_e32 v76, v19, v9
	v_mad_i64_i32 v[8:9], s[0:1], v16, s10, 0
	v_add_u32_e32 v12, s5, v12
	v_add_u32_e32 v14, s5, v14
	v_add_u32_e32 v16, 0x60, v16
	v_lshlrev_b32_e32 v80, 10, v19
	v_lshlrev_b32_e32 v81, 4, v20
	v_mad_i64_i32 v[0:1], s[0:1], v0, s10, 0
	v_mad_i64_i32 v[4:5], s[0:1], v4, s10, 0
	v_mad_i64_i32 v[6:7], s[0:1], v6, s10, 0
	v_mad_i64_i32 v[12:13], s[0:1], v12, s10, 0
	v_mad_i64_i32 v[14:15], s[0:1], v14, s10, 0
	v_mad_i64_i32 v[16:17], s[0:1], v16, s10, 0
	v_or_b32_e32 v19, v80, v81
	v_lshl_add_u64 v[0:1], v[0:1], 1, s[48:49]
	v_readfirstlane_b32 s0, v19
	v_lshl_add_u64 v[0:1], v[0:1], 0, v[124:125]
	s_mov_b32 m0, s0
	v_lshl_add_u64 v[4:5], v[4:5], 1, s[48:49]
	global_load_lds_dwordx4 v[0:1], off
	v_add_u32_e32 v0, 0x1000, v19
	v_readlane_b32 s8, v238, 8
	v_readfirstlane_b32 s0, v0
	v_add_u32_e32 v0, 0x2000, v19
	v_lshl_add_u64 v[4:5], v[4:5], 0, v[124:125]
	v_lshl_add_u64 v[6:7], v[6:7], 1, s[48:49]
	v_readlane_b32 s9, v238, 9
	v_add_u32_e32 v20, 0x6000, v19
	s_mov_b32 m0, s0
	v_readfirstlane_b32 s0, v0
	v_lshl_add_u64 v[6:7], v[6:7], 0, v[124:125]
	v_lshl_add_u64 v[8:9], v[8:9], 1, s[8:9]
	global_load_lds_dwordx4 v[4:5], off
	s_mov_b32 m0, s0
	v_readfirstlane_b32 s0, v20
	v_add_u32_e32 v0, 0x7000, v19
	v_lshl_add_u64 v[8:9], v[8:9], 0, v[124:125]
	v_lshl_add_u64 v[12:13], v[12:13], 1, s[8:9]
	global_load_lds_dwordx4 v[6:7], off
	s_mov_b32 m0, s0
	v_readfirstlane_b32 s0, v0
	v_add_u32_e32 v0, 0x8000, v19
	v_lshl_add_u64 v[12:13], v[12:13], 0, v[124:125]
	v_lshl_add_u64 v[14:15], v[14:15], 1, s[8:9]
	global_load_lds_dwordx4 v[8:9], off
	s_mov_b32 m0, s0
	v_readfirstlane_b32 s0, v0
	v_add_u32_e32 v0, 0x9000, v19
	v_lshl_add_u64 v[14:15], v[14:15], 0, v[124:125]
	v_lshl_add_u64 v[16:17], v[16:17], 1, s[8:9]
	global_load_lds_dwordx4 v[12:13], off
	s_mov_b32 m0, s0
	v_readfirstlane_b32 s0, v0
	v_lshl_add_u64 v[16:17], v[16:17], 0, v[124:125]
	global_load_lds_dwordx4 v[14:15], off
	s_mov_b32 m0, s0
	v_and_b32_e32 v78, 31, v18
	global_load_lds_dwordx4 v[16:17], off
	v_mul_i32_i24_e32 v79, 0x60, v24
	v_or_b32_e32 v1, v79, v78
	v_lshrrev_b32_e32 v25, 1, v18
	v_lshlrev_b32_e32 v82, 7, v1
	v_lshlrev_b32_e32 v1, 7, v78
	v_bfe_u32 v77, v18, 5, 1
	v_bfe_u32 v0, v18, 1, 3
	v_lshl_or_b32 v83, v76, 12, v1
	v_bitop3_b32 v1, v77, v25, 7 bitop3:0x78
	v_lshlrev_b32_e32 v84, 4, v1
	v_bitop3_b32 v1, v77, v0, 2 bitop3:0x36
	v_lshlrev_b32_e32 v85, 4, v1
	v_bitop3_b32 v1, v77, v0, 4 bitop3:0x36
	v_bitop3_b32 v0, v77, v0, 6 bitop3:0x36
	v_mov_b64_e32 v[10:11], s[8:9]
	v_lshlrev_b32_e32 v87, 4, v0
	v_bitop3_b32 v0, v23, 7, v18 bitop3:0x48
	s_mul_i32 s8, s43, 0x60
	v_lshlrev_b32_e32 v124, 4, v0
	v_or_b32_e32 v0, s8, v21
	v_add_u32_e32 v0, v0, v22
	s_mulk_i32 s7, 0x1800
	v_mov_b64_e32 v[2:3], s[48:49]
	v_subrev_u32_e32 v0, s7, v0
	v_readlane_b32 s9, v238, 18
	v_lshlrev_b32_e32 v86, 4, v1
	s_waitcnt vmcnt(0)
	v_mov_b32_e32 v32, 0
	v_mad_i64_i32 v[48:49], s[0:1], s9, v0, v[2:3]
	v_or_b32_e32 v0, 32, v21
	v_add3_u32 v1, v0, s8, v22
	v_subrev_u32_e32 v1, s7, v1
	v_mad_i64_i32 v[50:51], s[0:1], s9, v1, v[2:3]
	v_or_b32_e32 v1, 64, v21
	v_add3_u32 v4, v1, s8, v22
	v_or_b32_e32 v0, s5, v0
	v_subrev_u32_e32 v4, s7, v4
	v_add_u32_e32 v0, v0, v22
	v_mad_i64_i32 v[52:53], s[0:1], s9, v4, v[2:3]
	v_or_b32_e32 v2, s5, v21
	v_mad_i64_i32 v[56:57], s[0:1], s9, v0, v[10:11]
	v_or_b32_e32 v0, s5, v1
	v_add_u32_e32 v2, v2, v22
	v_add_u32_e32 v0, v0, v22
	v_mad_i64_i32 v[58:59], s[0:1], s9, v0, v[10:11]
	v_add_u32_e32 v0, 0x60, v2
	s_mov_b32 s6, 2
	v_mad_i64_i32 v[54:55], s[0:1], s9, v2, v[10:11]
	v_mad_i64_i32 v[60:61], s[0:1], s9, v0, v[10:11]
	v_mov_b32_e32 v33, v32
	v_mov_b32_e32 v34, v32
	v_mov_b32_e32 v35, v32
	v_mov_b32_e32 v36, v32
	v_mov_b32_e32 v37, v32
	v_mov_b32_e32 v38, v32
	v_mov_b32_e32 v39, v32
	v_mov_b32_e32 v40, v32
	v_mov_b32_e32 v41, v32
	v_mov_b32_e32 v42, v32
	v_mov_b32_e32 v43, v32
	v_mov_b32_e32 v44, v32
	v_mov_b32_e32 v45, v32
	v_mov_b32_e32 v46, v32
	v_mov_b32_e32 v47, v32
	v_mov_b32_e32 v16, v32
	v_mov_b32_e32 v17, v32
	v_mov_b32_e32 v18, v32
	v_mov_b32_e32 v19, v32
	v_mov_b32_e32 v20, v32
	v_mov_b32_e32 v21, v32
	v_mov_b32_e32 v22, v32
	v_mov_b32_e32 v23, v32
	v_mov_b32_e32 v24, v32
	v_mov_b32_e32 v25, v32
	v_mov_b32_e32 v26, v32
	v_mov_b32_e32 v27, v32
	s_waitcnt vmcnt(0)
	v_mov_b32_e32 v28, v32
	v_mov_b32_e32 v29, v32
	v_mov_b32_e32 v30, v32
	v_mov_b32_e32 v31, v32
	v_mov_b32_e32 v0, v32
	v_mov_b32_e32 v1, v32
	v_mov_b32_e32 v2, v32
	v_mov_b32_e32 v3, v32
	v_mov_b32_e32 v4, v32
	v_mov_b32_e32 v5, v32
	v_mov_b32_e32 v6, v32
	v_mov_b32_e32 v7, v32
	v_mov_b32_e32 v8, v32
	v_mov_b32_e32 v9, v32
	v_mov_b32_e32 v10, v32
	v_mov_b32_e32 v11, v32
	v_mov_b32_e32 v12, v32
	v_mov_b32_e32 v13, v32
	v_mov_b32_e32 v14, v32
	v_mov_b32_e32 v15, v32
	s_waitcnt lgkmcnt(0)
	s_barrier
	v_add_u32_e32 v134, v80, v81
	v_mov_b32_e32 v136, v124
	v_mov_b32_e32 v137, 0
	v_readfirstlane_b32 s101, v134
	v_lshl_add_u64 v[48:49], v[48:49], 0, v[136:137]
	v_lshl_add_u64 v[50:51], v[50:51], 0, v[136:137]
	v_lshl_add_u64 v[52:53], v[52:53], 0, v[136:137]
	v_lshl_add_u64 v[54:55], v[54:55], 0, v[136:137]
	v_lshl_add_u64 v[56:57], v[56:57], 0, v[136:137]
	v_lshl_add_u64 v[58:59], v[58:59], 0, v[136:137]
	v_lshl_add_u64 v[60:61], v[60:61], 0, v[136:137]
	v_and_b32_e32 v130, 15, v127
	v_bfe_u32 v131, v127, 4, 2
	v_bfe_u32 v132, v127, 1, 3
	v_xor_b32_e32 v133, v131, v132
	v_lshlrev_b32_e32 v133, 4, v133
	v_xor_b32_e32 v135, 64, v133
	v_lshlrev_b32_e32 v138, 7, v130
	v_lshrrev_b32_e32 v139, 6, v127
	v_lshl_add_u32 v139, v139, 5, v130
	v_lshlrev_b32_e32 v139, 7, v139
	v_add_u32_e32 v120, v138, v133
	v_add_u32_e32 v121, v138, v135
	v_add_u32_e32 v122, v139, v133
	v_add_u32_e32 v123, v139, v135
	v_lshl_add_u64 v[48:49], v[48:49], 0, s[2:3]
	v_lshl_add_u64 v[50:51], v[50:51], 0, s[2:3]
	v_lshl_add_u64 v[52:53], v[52:53], 0, s[2:3]
	v_lshl_add_u64 v[54:55], v[54:55], 0, s[2:3]
	v_lshl_add_u64 v[56:57], v[56:57], 0, s[2:3]
	v_lshl_add_u64 v[58:59], v[58:59], 0, s[2:3]
	v_lshl_add_u64 v[60:61], v[60:61], 0, s[2:3]
	ds_read_b128 v[88:91], v120 offset:0
	ds_read_b128 v[112:115], v122 offset:24576
	ds_read_b128 v[116:119], v122 offset:26624
	ds_read_b128 v[92:95], v120 offset:2048
	ds_read_b128 v[96:99], v120 offset:4096
	ds_read_b128 v[100:103], v120 offset:6144
	ds_read_b128 v[104:107], v120 offset:8192
	ds_read_b128 v[108:111], v120 offset:10240
	s_add_u32 m0, s101, 0x3000
	s_nop 0
	global_load_lds_dwordx4 v[48:49], off
	v_lshl_add_u64 v[48:49], v[48:49], 0, s[2:3]
	s_add_u32 m0, s101, 0x4000
	s_nop 0
	global_load_lds_dwordx4 v[50:51], off
	v_lshl_add_u64 v[50:51], v[50:51], 0, s[2:3]
	s_add_u32 m0, s101, 0x5000
	s_nop 0
	global_load_lds_dwordx4 v[52:53], off
	v_lshl_add_u64 v[52:53], v[52:53], 0, s[2:3]
	s_add_u32 m0, s101, 0xa000
	s_nop 0
	global_load_lds_dwordx4 v[54:55], off
	v_lshl_add_u64 v[54:55], v[54:55], 0, s[2:3]
	s_lshr_b32 s100, s42, 1
	s_add_i32 s100, s100, -1
.Lrs16_loop:
	s_waitcnt lgkmcnt(6)
	v_mfma_f32_16x16x32_bf16 v[0:3], v[88:91], v[112:115], v[0:3]
	s_add_u32 m0, s101, 0xb000
	ds_read_b128 v[182:185], v121 offset:0
	global_load_lds_dwordx4 v[56:57], off
	v_lshl_add_u64 v[56:57], v[56:57], 0, s[2:3]
	s_waitcnt lgkmcnt(6)
	v_mfma_f32_16x16x32_bf16 v[4:7], v[88:91], v[116:119], v[4:7]
	s_add_u32 m0, s101, 0xc000
	ds_read_b128 v[206:209], v123 offset:24576
	global_load_lds_dwordx4 v[58:59], off
	v_lshl_add_u64 v[58:59], v[58:59], 0, s[2:3]
	s_waitcnt lgkmcnt(6)
	v_mfma_f32_16x16x32_bf16 v[8:11], v[92:95], v[112:115], v[8:11]
	s_add_u32 m0, s101, 0xd000
	ds_read_b128 v[210:213], v123 offset:26624
	global_load_lds_dwordx4 v[60:61], off
	v_lshl_add_u64 v[60:61], v[60:61], 0, s[2:3]
	v_mfma_f32_16x16x32_bf16 v[12:15], v[92:95], v[116:119], v[12:15]
	ds_read_b128 v[186:189], v121 offset:2048
	s_waitcnt lgkmcnt(7)
	v_mfma_f32_16x16x32_bf16 v[16:19], v[96:99], v[112:115], v[16:19]
	ds_read_b128 v[190:193], v121 offset:4096
	v_mfma_f32_16x16x32_bf16 v[20:23], v[96:99], v[116:119], v[20:23]
	ds_read_b128 v[194:197], v121 offset:6144
	s_waitcnt lgkmcnt(8)
	v_mfma_f32_16x16x32_bf16 v[24:27], v[100:103], v[112:115], v[24:27]
	ds_read_b128 v[198:201], v121 offset:8192
	v_mfma_f32_16x16x32_bf16 v[28:31], v[100:103], v[116:119], v[28:31]
	ds_read_b128 v[202:205], v121 offset:10240
	s_waitcnt lgkmcnt(9)
	v_mfma_f32_16x16x32_bf16 v[32:35], v[104:107], v[112:115], v[32:35]
	v_mfma_f32_16x16x32_bf16 v[36:39], v[104:107], v[116:119], v[36:39]
	s_waitcnt lgkmcnt(8)
	v_mfma_f32_16x16x32_bf16 v[40:43], v[108:111], v[112:115], v[40:43]
	v_mfma_f32_16x16x32_bf16 v[44:47], v[108:111], v[116:119], v[44:47]
	s_waitcnt vmcnt(0) lgkmcnt(0)
	s_barrier
	v_mfma_f32_16x16x32_bf16 v[0:3], v[182:185], v[206:209], v[0:3]
	s_add_u32 m0, s101, 0x0
	ds_read_b128 v[88:91], v120 offset:12288
	global_load_lds_dwordx4 v[48:49], off
	v_lshl_add_u64 v[48:49], v[48:49], 0, s[2:3]
	v_mfma_f32_16x16x32_bf16 v[4:7], v[182:185], v[210:213], v[4:7]
	s_add_u32 m0, s101, 0x1000
	ds_read_b128 v[112:115], v122 offset:40960
	global_load_lds_dwordx4 v[50:51], off
	v_lshl_add_u64 v[50:51], v[50:51], 0, s[2:3]
	v_mfma_f32_16x16x32_bf16 v[8:11], v[186:189], v[206:209], v[8:11]
	s_add_u32 m0, s101, 0x2000
	ds_read_b128 v[116:119], v122 offset:43008
	global_load_lds_dwordx4 v[52:53], off
	v_lshl_add_u64 v[52:53], v[52:53], 0, s[2:3]
	v_mfma_f32_16x16x32_bf16 v[12:15], v[186:189], v[210:213], v[12:15]
	s_add_u32 m0, s101, 0x6000
	ds_read_b128 v[92:95], v120 offset:14336
	global_load_lds_dwordx4 v[54:55], off
	v_lshl_add_u64 v[54:55], v[54:55], 0, s[2:3]
	v_mfma_f32_16x16x32_bf16 v[16:19], v[190:193], v[206:209], v[16:19]
	ds_read_b128 v[96:99], v120 offset:16384
	v_mfma_f32_16x16x32_bf16 v[20:23], v[190:193], v[210:213], v[20:23]
	ds_read_b128 v[100:103], v120 offset:18432
	v_mfma_f32_16x16x32_bf16 v[24:27], v[194:197], v[206:209], v[24:27]
	ds_read_b128 v[104:107], v120 offset:20480
	v_mfma_f32_16x16x32_bf16 v[28:31], v[194:197], v[210:213], v[28:31]
	ds_read_b128 v[108:111], v120 offset:22528
	v_mfma_f32_16x16x32_bf16 v[32:35], v[198:201], v[206:209], v[32:35]
	v_mfma_f32_16x16x32_bf16 v[36:39], v[198:201], v[210:213], v[36:39]
	v_mfma_f32_16x16x32_bf16 v[40:43], v[202:205], v[206:209], v[40:43]
	v_mfma_f32_16x16x32_bf16 v[44:47], v[202:205], v[210:213], v[44:47]
	s_waitcnt lgkmcnt(6)
	v_mfma_f32_16x16x32_bf16 v[0:3], v[88:91], v[112:115], v[0:3]
	s_add_u32 m0, s101, 0x7000
	ds_read_b128 v[182:185], v121 offset:12288
	global_load_lds_dwordx4 v[56:57], off
	v_lshl_add_u64 v[56:57], v[56:57], 0, s[2:3]
	s_waitcnt lgkmcnt(6)
	v_mfma_f32_16x16x32_bf16 v[4:7], v[88:91], v[116:119], v[4:7]
	s_add_u32 m0, s101, 0x8000
	ds_read_b128 v[206:209], v123 offset:40960
	global_load_lds_dwordx4 v[58:59], off
	v_lshl_add_u64 v[58:59], v[58:59], 0, s[2:3]
	s_waitcnt lgkmcnt(6)
	v_mfma_f32_16x16x32_bf16 v[8:11], v[92:95], v[112:115], v[8:11]
	s_add_u32 m0, s101, 0x9000
	ds_read_b128 v[210:213], v123 offset:43008
	global_load_lds_dwordx4 v[60:61], off
	v_lshl_add_u64 v[60:61], v[60:61], 0, s[2:3]
	v_mfma_f32_16x16x32_bf16 v[12:15], v[92:95], v[116:119], v[12:15]
	ds_read_b128 v[186:189], v121 offset:14336
	s_waitcnt lgkmcnt(7)
	v_mfma_f32_16x16x32_bf16 v[16:19], v[96:99], v[112:115], v[16:19]
	ds_read_b128 v[190:193], v121 offset:16384
	v_mfma_f32_16x16x32_bf16 v[20:23], v[96:99], v[116:119], v[20:23]
	ds_read_b128 v[194:197], v121 offset:18432
	s_waitcnt lgkmcnt(8)
	v_mfma_f32_16x16x32_bf16 v[24:27], v[100:103], v[112:115], v[24:27]
	ds_read_b128 v[198:201], v121 offset:20480
	v_mfma_f32_16x16x32_bf16 v[28:31], v[100:103], v[116:119], v[28:31]
	ds_read_b128 v[202:205], v121 offset:22528
	s_waitcnt lgkmcnt(9)
	v_mfma_f32_16x16x32_bf16 v[32:35], v[104:107], v[112:115], v[32:35]
	v_mfma_f32_16x16x32_bf16 v[36:39], v[104:107], v[116:119], v[36:39]
	s_waitcnt lgkmcnt(8)
	v_mfma_f32_16x16x32_bf16 v[40:43], v[108:111], v[112:115], v[40:43]
	v_mfma_f32_16x16x32_bf16 v[44:47], v[108:111], v[116:119], v[44:47]
	s_waitcnt vmcnt(0) lgkmcnt(0)
	s_barrier
	v_mfma_f32_16x16x32_bf16 v[0:3], v[182:185], v[206:209], v[0:3]
	s_add_u32 m0, s101, 0x3000
	ds_read_b128 v[88:91], v120 offset:0
	global_load_lds_dwordx4 v[48:49], off
	v_lshl_add_u64 v[48:49], v[48:49], 0, s[2:3]
	v_mfma_f32_16x16x32_bf16 v[4:7], v[182:185], v[210:213], v[4:7]
	s_add_u32 m0, s101, 0x4000
	ds_read_b128 v[112:115], v122 offset:24576
	global_load_lds_dwordx4 v[50:51], off
	v_lshl_add_u64 v[50:51], v[50:51], 0, s[2:3]
	v_mfma_f32_16x16x32_bf16 v[8:11], v[186:189], v[206:209], v[8:11]
	s_add_u32 m0, s101, 0x5000
	ds_read_b128 v[116:119], v122 offset:26624
	global_load_lds_dwordx4 v[52:53], off
	v_lshl_add_u64 v[52:53], v[52:53], 0, s[2:3]
	v_mfma_f32_16x16x32_bf16 v[12:15], v[186:189], v[210:213], v[12:15]
	s_add_u32 m0, s101, 0xa000
	ds_read_b128 v[92:95], v120 offset:2048
	global_load_lds_dwordx4 v[54:55], off
	v_lshl_add_u64 v[54:55], v[54:55], 0, s[2:3]
	v_mfma_f32_16x16x32_bf16 v[16:19], v[190:193], v[206:209], v[16:19]
	ds_read_b128 v[96:99], v120 offset:4096
	v_mfma_f32_16x16x32_bf16 v[20:23], v[190:193], v[210:213], v[20:23]
	ds_read_b128 v[100:103], v120 offset:6144
	v_mfma_f32_16x16x32_bf16 v[24:27], v[194:197], v[206:209], v[24:27]
	ds_read_b128 v[104:107], v120 offset:8192
	v_mfma_f32_16x16x32_bf16 v[28:31], v[194:197], v[210:213], v[28:31]
	ds_read_b128 v[108:111], v120 offset:10240
	v_mfma_f32_16x16x32_bf16 v[32:35], v[198:201], v[206:209], v[32:35]
	v_mfma_f32_16x16x32_bf16 v[36:39], v[198:201], v[210:213], v[36:39]
	v_mfma_f32_16x16x32_bf16 v[40:43], v[202:205], v[206:209], v[40:43]
	v_mfma_f32_16x16x32_bf16 v[44:47], v[202:205], v[210:213], v[44:47]
	s_add_i32 s100, s100, -1
	s_cmp_lg_u32 s100, 0
	s_cbranch_scc1 .Lrs16_loop
	s_waitcnt lgkmcnt(6)
	v_mfma_f32_16x16x32_bf16 v[0:3], v[88:91], v[112:115], v[0:3]
	s_add_u32 m0, s101, 0xb000
	ds_read_b128 v[182:185], v121 offset:0
	global_load_lds_dwordx4 v[56:57], off
	v_lshl_add_u64 v[56:57], v[56:57], 0, s[2:3]
	s_waitcnt lgkmcnt(6)
	v_mfma_f32_16x16x32_bf16 v[4:7], v[88:91], v[116:119], v[4:7]
	s_add_u32 m0, s101, 0xc000
	ds_read_b128 v[206:209], v123 offset:24576
	global_load_lds_dwordx4 v[58:59], off
	v_lshl_add_u64 v[58:59], v[58:59], 0, s[2:3]
	s_waitcnt lgkmcnt(6)
	v_mfma_f32_16x16x32_bf16 v[8:11], v[92:95], v[112:115], v[8:11]
	s_add_u32 m0, s101, 0xd000
	ds_read_b128 v[210:213], v123 offset:26624
	global_load_lds_dwordx4 v[60:61], off
	v_lshl_add_u64 v[60:61], v[60:61], 0, s[2:3]
	v_mfma_f32_16x16x32_bf16 v[12:15], v[92:95], v[116:119], v[12:15]
	ds_read_b128 v[186:189], v121 offset:2048
	s_waitcnt lgkmcnt(7)
	v_mfma_f32_16x16x32_bf16 v[16:19], v[96:99], v[112:115], v[16:19]
	ds_read_b128 v[190:193], v121 offset:4096
	v_mfma_f32_16x16x32_bf16 v[20:23], v[96:99], v[116:119], v[20:23]
	ds_read_b128 v[194:197], v121 offset:6144
	s_waitcnt lgkmcnt(8)
	v_mfma_f32_16x16x32_bf16 v[24:27], v[100:103], v[112:115], v[24:27]
	ds_read_b128 v[198:201], v121 offset:8192
	v_mfma_f32_16x16x32_bf16 v[28:31], v[100:103], v[116:119], v[28:31]
	ds_read_b128 v[202:205], v121 offset:10240
	s_waitcnt lgkmcnt(9)
	v_mfma_f32_16x16x32_bf16 v[32:35], v[104:107], v[112:115], v[32:35]
	v_mfma_f32_16x16x32_bf16 v[36:39], v[104:107], v[116:119], v[36:39]
	s_waitcnt lgkmcnt(8)
	v_mfma_f32_16x16x32_bf16 v[40:43], v[108:111], v[112:115], v[40:43]
	v_mfma_f32_16x16x32_bf16 v[44:47], v[108:111], v[116:119], v[44:47]
	s_waitcnt vmcnt(0) lgkmcnt(0)
	s_barrier
	v_mfma_f32_16x16x32_bf16 v[0:3], v[182:185], v[206:209], v[0:3]
	ds_read_b128 v[88:91], v120 offset:12288
	v_mfma_f32_16x16x32_bf16 v[4:7], v[182:185], v[210:213], v[4:7]
	ds_read_b128 v[112:115], v122 offset:40960
	v_mfma_f32_16x16x32_bf16 v[8:11], v[186:189], v[206:209], v[8:11]
	ds_read_b128 v[116:119], v122 offset:43008
	v_mfma_f32_16x16x32_bf16 v[12:15], v[186:189], v[210:213], v[12:15]
	ds_read_b128 v[92:95], v120 offset:14336
	v_mfma_f32_16x16x32_bf16 v[16:19], v[190:193], v[206:209], v[16:19]
	ds_read_b128 v[96:99], v120 offset:16384
	v_mfma_f32_16x16x32_bf16 v[20:23], v[190:193], v[210:213], v[20:23]
	ds_read_b128 v[100:103], v120 offset:18432
	v_mfma_f32_16x16x32_bf16 v[24:27], v[194:197], v[206:209], v[24:27]
	ds_read_b128 v[104:107], v120 offset:20480
	v_mfma_f32_16x16x32_bf16 v[28:31], v[194:197], v[210:213], v[28:31]
	ds_read_b128 v[108:111], v120 offset:22528
	v_mfma_f32_16x16x32_bf16 v[32:35], v[198:201], v[206:209], v[32:35]
	v_mfma_f32_16x16x32_bf16 v[36:39], v[198:201], v[210:213], v[36:39]
	v_mfma_f32_16x16x32_bf16 v[40:43], v[202:205], v[206:209], v[40:43]
	v_mfma_f32_16x16x32_bf16 v[44:47], v[202:205], v[210:213], v[44:47]
	s_waitcnt lgkmcnt(6)
	v_mfma_f32_16x16x32_bf16 v[0:3], v[88:91], v[112:115], v[0:3]
	ds_read_b128 v[182:185], v121 offset:12288
	s_waitcnt lgkmcnt(6)
	v_mfma_f32_16x16x32_bf16 v[4:7], v[88:91], v[116:119], v[4:7]
	ds_read_b128 v[206:209], v123 offset:40960
	s_waitcnt lgkmcnt(6)
	v_mfma_f32_16x16x32_bf16 v[8:11], v[92:95], v[112:115], v[8:11]
	ds_read_b128 v[210:213], v123 offset:43008
	v_mfma_f32_16x16x32_bf16 v[12:15], v[92:95], v[116:119], v[12:15]
	ds_read_b128 v[186:189], v121 offset:14336
	s_waitcnt lgkmcnt(7)
	v_mfma_f32_16x16x32_bf16 v[16:19], v[96:99], v[112:115], v[16:19]
	ds_read_b128 v[190:193], v121 offset:16384
	v_mfma_f32_16x16x32_bf16 v[20:23], v[96:99], v[116:119], v[20:23]
	ds_read_b128 v[194:197], v121 offset:18432
	s_waitcnt lgkmcnt(8)
	v_mfma_f32_16x16x32_bf16 v[24:27], v[100:103], v[112:115], v[24:27]
	ds_read_b128 v[198:201], v121 offset:20480
	v_mfma_f32_16x16x32_bf16 v[28:31], v[100:103], v[116:119], v[28:31]
	ds_read_b128 v[202:205], v121 offset:22528
	s_waitcnt lgkmcnt(9)
	v_mfma_f32_16x16x32_bf16 v[32:35], v[104:107], v[112:115], v[32:35]
	v_mfma_f32_16x16x32_bf16 v[36:39], v[104:107], v[116:119], v[36:39]
	s_waitcnt lgkmcnt(8)
	v_mfma_f32_16x16x32_bf16 v[40:43], v[108:111], v[112:115], v[40:43]
	v_mfma_f32_16x16x32_bf16 v[44:47], v[108:111], v[116:119], v[44:47]
	s_waitcnt vmcnt(0) lgkmcnt(0)
	s_barrier
	v_mfma_f32_16x16x32_bf16 v[0:3], v[182:185], v[206:209], v[0:3]
	v_mfma_f32_16x16x32_bf16 v[4:7], v[182:185], v[210:213], v[4:7]
	v_mfma_f32_16x16x32_bf16 v[8:11], v[186:189], v[206:209], v[8:11]
	v_mfma_f32_16x16x32_bf16 v[12:15], v[186:189], v[210:213], v[12:15]
	v_mfma_f32_16x16x32_bf16 v[16:19], v[190:193], v[206:209], v[16:19]
	v_mfma_f32_16x16x32_bf16 v[20:23], v[190:193], v[210:213], v[20:23]
	v_mfma_f32_16x16x32_bf16 v[24:27], v[194:197], v[206:209], v[24:27]
	v_mfma_f32_16x16x32_bf16 v[28:31], v[194:197], v[210:213], v[28:31]
	v_mfma_f32_16x16x32_bf16 v[32:35], v[198:201], v[206:209], v[32:35]
	v_mfma_f32_16x16x32_bf16 v[36:39], v[198:201], v[210:213], v[36:39]
	v_mfma_f32_16x16x32_bf16 v[40:43], v[202:205], v[206:209], v[40:43]
	v_mfma_f32_16x16x32_bf16 v[44:47], v[202:205], v[210:213], v[44:47]
	s_nop 7
	s_nop 7
	s_branch .Lrs16_epi
